# static priority in two GEMM mainloops instead of hipcc per-phase flips: P7 raise for waves 4-7, P8 raise for waves 0-3 (A/B per phase; P1 and P6 keep their flips)
# speedup vs baseline: 1.1200x; 1.0010x over previous
; #define PG8_STAGE(bufoff, gbase, voff) do { _Pragma("unroll") for (int _i = 0; _i < 2; ++_i) \
;         __builtin_amdgcn_global_load_lds((const unsigned*)((const char*)(gbase) + (voff)[_i]), (LAS unsigned*)(lds + (bufoff) + ldsw + _i * 8192), 16, 0, 0); } while (0)
; #define PG8_LDA(dst, b, h) do { _Pragma("unroll") for (int m = 0; m < 4; ++m) _Pragma("unroll") for (int k = 0; k < 2; ++k) dst[m][k] = *(const LAS bf16x8*)(lds + PG8_SA(b, h) + aoff + m * 2048 + k * 1024); } while (0)
; #define PG8_LDB(dst, b, h) do { _Pragma("unroll") for (int n = 0; n < 2; ++n) _Pragma("unroll") for (int k = 0; k < 2; ++k) dst[n][k] = *(const LAS bf16x8*)(lds + PG8_SB(b, h) + boff + n * 2048 + k * 1024); } while (0)
; #define PG8_MMA(ai, bj, At, Bt) do { __builtin_amdgcn_s_setprio(1); _Pragma("unroll") for (int m = 0; m < 4; ++m) _Pragma("unroll") for (int n = 0; n < 2; ++n) _Pragma("unroll") for (int k = 0; k < 2; ++k) \
;         acc[ai][bj][m][n] = __builtin_amdgcn_mfma_f32_16x16x32_bf16(Bt[n][k], At[m][k], acc[ai][bj][m][n], 0, 0, 0); __builtin_amdgcn_s_setprio(0); } while (0)
; #define PG8_WAIT_L(n) asm volatile("s_waitcnt lgkmcnt(" #n ")" ::: "memory")
; #define PG8_BAR __builtin_amdgcn_s_barrier()
; #define PG8_SCHED __builtin_amdgcn_sched_barrier(0)
; template <class Epi, class Sched>
; __device__ __forceinline__ void gemm_phase(LAS unsigned char* lds, const Gemm g, const Sched& S, const Epi& E) {
;     ...
;             PG8_LDB(B0, 0, 0); PG8_SCHED; PG8_LDA(At, 0, 0); PG8_STAGE(PG8_SA(1, 1), a1 + hstepA, voffA);
;             PG8_WAIT_L(8); PG8_BAR; PG8_WAIT_L(0); PG8_MMA(0, 0, At, B0); PG8_BAR; PG8_SCHED;
;     ...
; #pragma unroll
;         for (int a = 0; a < 2; ++a)
; #pragma unroll
;             for (int b = 0; b < 2; ++b)
; #pragma unroll
;                 for (int m = 0; m < 4; ++m)
; #pragma unroll
;                     for (int n = 0; n < 2; ++n) acc[a][b][m][n] = (f32x4){0.f, 0.f, 0.f, 0.f};
;         cur = nxt; cA = nA; cB = nB; ++ui;
.LBB0_1288:
	s_add_u32 s26, s26, 0x160080
	s_addc_u32 s27, s27, 0
	s_add_u32 s4, s36, 0x100
	v_mov_b32_e32 v0, 0
	s_addc_u32 s5, s37, 0
	s_mov_b32 s55, -2
	v_mov_b32_e32 v1, v0
	v_mov_b32_e32 v2, v0
	v_mov_b32_e32 v3, v0
	v_mov_b32_e32 v4, v0
	v_mov_b32_e32 v5, v0
	v_mov_b32_e32 v6, v0
	v_mov_b32_e32 v7, v0
	v_mov_b32_e32 v16, v0
	v_mov_b32_e32 v17, v0
	v_mov_b32_e32 v18, v0
	v_mov_b32_e32 v19, v0
	v_mov_b32_e32 v20, v0
	v_mov_b32_e32 v21, v0
	v_mov_b32_e32 v22, v0
	v_mov_b32_e32 v23, v0
	v_mov_b32_e32 v32, v0
	v_mov_b32_e32 v33, v0
	v_mov_b32_e32 v34, v0
	v_mov_b32_e32 v35, v0
	v_mov_b32_e32 v36, v0
	v_mov_b32_e32 v37, v0
	v_mov_b32_e32 v38, v0
	v_mov_b32_e32 v39, v0
	v_mov_b32_e32 v48, v0
	v_mov_b32_e32 v49, v0
	v_mov_b32_e32 v50, v0
	v_mov_b32_e32 v51, v0
	v_mov_b32_e32 v52, v0
	v_mov_b32_e32 v53, v0
	v_mov_b32_e32 v54, v0
	v_mov_b32_e32 v55, v0
	v_mov_b32_e32 v8, v0
	v_mov_b32_e32 v9, v0
	v_mov_b32_e32 v10, v0
	v_mov_b32_e32 v11, v0
	v_mov_b32_e32 v12, v0
	v_mov_b32_e32 v13, v0
	v_mov_b32_e32 v14, v0
	v_mov_b32_e32 v15, v0
	v_mov_b32_e32 v24, v0
	v_mov_b32_e32 v25, v0
	v_mov_b32_e32 v26, v0
	v_mov_b32_e32 v27, v0
	v_mov_b32_e32 v28, v0
	v_mov_b32_e32 v29, v0
	v_mov_b32_e32 v30, v0
	v_mov_b32_e32 v31, v0
	v_mov_b32_e32 v40, v0
	v_mov_b32_e32 v41, v0
	v_mov_b32_e32 v42, v0
	v_mov_b32_e32 v43, v0
	v_mov_b32_e32 v44, v0
	v_mov_b32_e32 v45, v0
	v_mov_b32_e32 v46, v0
	v_mov_b32_e32 v47, v0
	v_mov_b32_e32 v56, v0
	v_mov_b32_e32 v57, v0
	v_mov_b32_e32 v58, v0
	v_mov_b32_e32 v59, v0
	v_mov_b32_e32 v60, v0
	v_mov_b32_e32 v61, v0
	v_mov_b32_e32 v62, v0
	v_mov_b32_e32 v63, v0
	v_mov_b32_e32 v64, v0
	v_mov_b32_e32 v65, v0
	v_mov_b32_e32 v66, v0
	v_mov_b32_e32 v67, v0
	v_mov_b32_e32 v68, v0
	v_mov_b32_e32 v69, v0
	v_mov_b32_e32 v70, v0
	v_mov_b32_e32 v71, v0
	v_mov_b32_e32 v80, v0
	v_mov_b32_e32 v81, v0
	v_mov_b32_e32 v82, v0
	v_mov_b32_e32 v83, v0
	v_mov_b32_e32 v84, v0
	v_mov_b32_e32 v85, v0
	v_mov_b32_e32 v86, v0
	v_mov_b32_e32 v87, v0
	v_mov_b32_e32 v96, v0
	v_mov_b32_e32 v97, v0
	v_mov_b32_e32 v98, v0
	v_mov_b32_e32 v99, v0
	v_mov_b32_e32 v100, v0
	v_mov_b32_e32 v101, v0
	v_mov_b32_e32 v102, v0
	v_mov_b32_e32 v103, v0
	v_mov_b32_e32 v112, v0
	v_mov_b32_e32 v113, v0
	v_mov_b32_e32 v114, v0
	v_mov_b32_e32 v115, v0
	v_mov_b32_e32 v116, v0
	v_mov_b32_e32 v117, v0
	v_mov_b32_e32 v118, v0
	v_mov_b32_e32 v119, v0
	v_mov_b32_e32 v72, v0
	v_mov_b32_e32 v73, v0
	v_mov_b32_e32 v74, v0
	v_mov_b32_e32 v75, v0
	v_mov_b32_e32 v76, v0
	v_mov_b32_e32 v77, v0
	v_mov_b32_e32 v78, v0
	v_mov_b32_e32 v79, v0
	v_mov_b32_e32 v88, v0
	v_mov_b32_e32 v89, v0
	v_mov_b32_e32 v90, v0
	v_mov_b32_e32 v91, v0
	v_mov_b32_e32 v92, v0
	v_mov_b32_e32 v93, v0
	v_mov_b32_e32 v94, v0
	v_mov_b32_e32 v95, v0
	v_mov_b32_e32 v104, v0
	v_mov_b32_e32 v105, v0
	v_mov_b32_e32 v106, v0
	v_mov_b32_e32 v107, v0
	v_mov_b32_e32 v108, v0
	v_mov_b32_e32 v109, v0
	v_mov_b32_e32 v110, v0
	v_mov_b32_e32 v111, v0
	v_mov_b32_e32 v120, v0
	v_mov_b32_e32 v121, v0
	v_mov_b32_e32 v122, v0
	v_mov_b32_e32 v123, v0
	v_mov_b32_e32 v124, v0
	v_mov_b32_e32 v125, v0
	v_mov_b32_e32 v126, v0
	v_mov_b32_e32 v127, v0
	v_readfirstlane_b32 vcc_lo, v196
	s_nop 3
	s_lshr_b32 vcc_lo, vcc_lo, 8
	s_cmp_lg_u32 vcc_lo, 0
	s_cbranch_scc1 .Lp8_prio_done
	s_setprio 1
.Lp8_prio_done:
.LBB0_1289:
	ds_read_b128 v[140:143], v151
	ds_read_b128 v[154:157], v151 offset:1024
	ds_read_b128 v[158:161], v151 offset:2048
	ds_read_b128 v[162:165], v151 offset:3072
	s_add_u32 s36, s26, 0xffea0080
	s_addc_u32 s37, s27, -1
	s_cmpk_eq_i32 s55, 0x54
	s_cselect_b32 s39, s9, s37
	s_cselect_b32 s38, s8, s36
	s_cselect_b32 s37, s11, s5
	s_cselect_b32 s36, s10, s4
	v_lshl_add_u64 v[144:145], s[26:27], 0, v[132:133]
	s_add_i32 m0, s23, 0xc000
	ds_read_b128 v[166:169], v152
	ds_read_b128 v[170:173], v152 offset:1024
	ds_read_b128 v[174:177], v152 offset:2048
	ds_read_b128 v[190:193], v152 offset:3072
	ds_read_b128 v[198:201], v152 offset:4096
	ds_read_b128 v[202:205], v152 offset:5120
	ds_read_b128 v[206:209], v152 offset:6144
	ds_read_b128 v[210:213], v152 offset:7168
	global_load_lds_dwordx4 v[144:145], off
	v_lshl_add_u64 v[144:145], s[26:27], 0, v[134:135]
	s_add_i32 m0, s23, 0xe000
	s_nop 0
	global_load_lds_dwordx4 v[144:145], off
	s_waitcnt lgkmcnt(8)
	s_barrier
	s_waitcnt lgkmcnt(0)
	s_waitcnt lgkmcnt(0)
	v_mfma_f32_16x16x32_bf16 v[124:127], v[140:143], v[166:169], v[124:127]
	v_mfma_f32_16x16x32_bf16 v[120:123], v[158:161], v[166:169], v[120:123]
	v_mfma_f32_16x16x32_bf16 v[108:111], v[140:143], v[174:177], v[108:111]
	v_mfma_f32_16x16x32_bf16 v[104:107], v[158:161], v[174:177], v[104:107]
	v_mfma_f32_16x16x32_bf16 v[92:95], v[140:143], v[198:201], v[92:95]
	v_mfma_f32_16x16x32_bf16 v[88:91], v[158:161], v[198:201], v[88:91]
	v_mfma_f32_16x16x32_bf16 v[76:79], v[140:143], v[206:209], v[76:79]
	v_mfma_f32_16x16x32_bf16 v[72:75], v[158:161], v[206:209], v[72:75]
	v_mfma_f32_16x16x32_bf16 v[124:127], v[154:157], v[170:173], v[124:127]
	v_mfma_f32_16x16x32_bf16 v[120:123], v[162:165], v[170:173], v[120:123]
	v_mfma_f32_16x16x32_bf16 v[108:111], v[154:157], v[190:193], v[108:111]
	v_mfma_f32_16x16x32_bf16 v[104:107], v[162:165], v[190:193], v[104:107]
	v_mfma_f32_16x16x32_bf16 v[92:95], v[154:157], v[202:205], v[92:95]
	v_mfma_f32_16x16x32_bf16 v[88:91], v[162:165], v[202:205], v[88:91]
	v_mfma_f32_16x16x32_bf16 v[76:79], v[154:157], v[210:213], v[76:79]
	v_mfma_f32_16x16x32_bf16 v[72:75], v[162:165], v[210:213], v[72:75]
	s_barrier
; #define PG8_STAGE(bufoff, gbase, voff) do { _Pragma("unroll") for (int _i = 0; _i < 2; ++_i) \
;         __builtin_amdgcn_global_load_lds((const unsigned*)((const char*)(gbase) + (voff)[_i]), (LAS unsigned*)(lds + (bufoff) + ldsw + _i * 8192), 16, 0, 0); } while (0)
; #define PG8_LDA(dst, b, h) do { _Pragma("unroll") for (int m = 0; m < 4; ++m) _Pragma("unroll") for (int k = 0; k < 2; ++k) dst[m][k] = *(const LAS bf16x8*)(lds + PG8_SA(b, h) + aoff + m * 2048 + k * 1024); } while (0)
; #define PG8_LDB(dst, b, h) do { _Pragma("unroll") for (int n = 0; n < 2; ++n) _Pragma("unroll") for (int k = 0; k < 2; ++k) dst[n][k] = *(const LAS bf16x8*)(lds + PG8_SB(b, h) + boff + n * 2048 + k * 1024); } while (0)
; #define PG8_WAIT_V(n) asm volatile("s_waitcnt vmcnt(" #n ")" ::: "memory")
; #define PG8_WAIT_L(n) asm volatile("s_waitcnt lgkmcnt(" #n ")" ::: "memory")
; #define PG8_BAR __builtin_amdgcn_s_barrier()
; #define PG8_SCHED __builtin_amdgcn_sched_barrier(0)
; template <class Epi, class Sched>
; __device__ __forceinline__ void gemm_phase(LAS unsigned char* lds, const Gemm g, const Sched& S, const Epi& E) {
;     ...
;             PG8_LDB(B0, 0, 0); PG8_SCHED; PG8_LDA(At, 0, 0); PG8_STAGE(PG8_SA(1, 1), a1 + hstepA, voffA);
;             PG8_WAIT_L(8); PG8_BAR; PG8_WAIT_L(0); PG8_MMA(0, 0, At, B0); PG8_BAR; PG8_SCHED;
;             PG8_LDB(B1, 0, 1); PG8_STAGE(PG8_SB(0, 0), b2, voffB);
;             PG8_BAR; PG8_WAIT_L(0); PG8_MMA(0, 1, At, B1); PG8_BAR;
;             PG8_LDA(At, 0, 1); PG8_STAGE(PG8_SA(0, 0), a2, voffA);
;             PG8_BAR; PG8_WAIT_L(0); PG8_MMA(1, 0, At, B0); PG8_BAR; PG8_SCHED;
;             PG8_STAGE(PG8_SB(0, 1), b2 + hstepB, voffB);
;             PG8_WAIT_V(6); PG8_BAR; PG8_MMA(1, 1, At, B1); PG8_BAR;
;             PG8_LDB(B0, 1, 0); PG8_SCHED; PG8_LDA(At, 1, 0); PG8_STAGE(PG8_SA(0, 1), a2 + hstepA, voffA);
;             PG8_WAIT_L(8); PG8_BAR; PG8_WAIT_L(0); PG8_MMA(0, 0, At, B0); PG8_BAR; PG8_SCHED;
;             PG8_LDB(B1, 1, 1); PG8_STAGE(PG8_SB(1, 0), b3, voffB);
;             PG8_BAR; PG8_WAIT_L(0); PG8_MMA(0, 1, At, B1); PG8_BAR;
;             PG8_LDA(At, 1, 1); PG8_STAGE(PG8_SA(1, 0), a3, voffA);
;             PG8_BAR; PG8_WAIT_L(0); PG8_MMA(1, 0, At, B0); PG8_BAR; PG8_SCHED;
;             PG8_STAGE(PG8_SB(1, 1), b3 + hstepB, voffB);
;             PG8_WAIT_V(6); PG8_BAR; PG8_MMA(1, 1, At, B1); PG8_BAR;
	s_add_i32 s56, s41, s22
	v_lshl_add_u64 v[144:145], s[36:37], 0, v[128:129]
	s_mov_b32 m0, s56
	ds_read_b128 v[214:217], v153
	ds_read_b128 v[218:221], v153 offset:1024
	ds_read_b128 v[222:225], v153 offset:2048
	ds_read_b128 v[226:229], v153 offset:3072
	global_load_lds_dwordx4 v[144:145], off
	v_lshl_add_u64 v[178:179], s[36:37], 0, v[130:131]
	s_add_i32 m0, s56, 0x2000
	s_nop 0
	global_load_lds_dwordx4 v[178:179], off
	s_barrier
	s_waitcnt lgkmcnt(0)
	s_waitcnt lgkmcnt(0)
	v_mfma_f32_16x16x32_bf16 v[116:119], v[214:217], v[166:169], v[116:119]
	v_mfma_f32_16x16x32_bf16 v[112:115], v[222:225], v[166:169], v[112:115]
	v_mfma_f32_16x16x32_bf16 v[100:103], v[214:217], v[174:177], v[100:103]
	v_mfma_f32_16x16x32_bf16 v[96:99], v[222:225], v[174:177], v[96:99]
	v_mfma_f32_16x16x32_bf16 v[84:87], v[214:217], v[198:201], v[84:87]
	v_mfma_f32_16x16x32_bf16 v[80:83], v[222:225], v[198:201], v[80:83]
	v_mfma_f32_16x16x32_bf16 v[68:71], v[214:217], v[206:209], v[68:71]
	v_mfma_f32_16x16x32_bf16 v[64:67], v[222:225], v[206:209], v[64:67]
	v_mfma_f32_16x16x32_bf16 v[116:119], v[218:221], v[170:173], v[116:119]
	v_mfma_f32_16x16x32_bf16 v[112:115], v[226:229], v[170:173], v[112:115]
	v_mfma_f32_16x16x32_bf16 v[100:103], v[218:221], v[190:193], v[100:103]
	v_mfma_f32_16x16x32_bf16 v[96:99], v[226:229], v[190:193], v[96:99]
	v_mfma_f32_16x16x32_bf16 v[84:87], v[218:221], v[202:205], v[84:87]
	v_mfma_f32_16x16x32_bf16 v[80:83], v[226:229], v[202:205], v[80:83]
	v_mfma_f32_16x16x32_bf16 v[68:71], v[218:221], v[210:213], v[68:71]
	v_mfma_f32_16x16x32_bf16 v[64:67], v[226:229], v[210:213], v[64:67]
	s_mov_b32 m0, s23
	v_lshl_add_u64 v[194:195], s[38:39], 0, v[128:129]
	s_barrier
	ds_read_b128 v[166:169], v152 offset:16384
	ds_read_b128 v[170:173], v152 offset:17408
	ds_read_b128 v[174:177], v152 offset:18432
	ds_read_b128 v[190:193], v152 offset:19456
	ds_read_b128 v[198:201], v152 offset:20480
	ds_read_b128 v[202:205], v152 offset:21504
	ds_read_b128 v[206:209], v152 offset:22528
	ds_read_b128 v[210:213], v152 offset:23552
	global_load_lds_dwordx4 v[194:195], off
	v_lshl_add_u64 v[230:231], s[38:39], 0, v[130:131]
	s_mov_b32 m0, s29
	s_nop 0
	global_load_lds_dwordx4 v[230:231], off
	s_barrier
	s_waitcnt lgkmcnt(0)
	s_waitcnt lgkmcnt(0)
	v_mfma_f32_16x16x32_bf16 v[60:63], v[140:143], v[166:169], v[60:63]
	v_mfma_f32_16x16x32_bf16 v[56:59], v[158:161], v[166:169], v[56:59]
	v_mfma_f32_16x16x32_bf16 v[44:47], v[140:143], v[174:177], v[44:47]
	v_mfma_f32_16x16x32_bf16 v[40:43], v[158:161], v[174:177], v[40:43]
	v_mfma_f32_16x16x32_bf16 v[28:31], v[140:143], v[198:201], v[28:31]
	v_mfma_f32_16x16x32_bf16 v[24:27], v[158:161], v[198:201], v[24:27]
	v_mfma_f32_16x16x32_bf16 v[12:15], v[140:143], v[206:209], v[12:15]
	v_mfma_f32_16x16x32_bf16 v[8:11], v[158:161], v[206:209], v[8:11]
	v_mfma_f32_16x16x32_bf16 v[60:63], v[154:157], v[170:173], v[60:63]
	v_mfma_f32_16x16x32_bf16 v[56:59], v[162:165], v[170:173], v[56:59]
	v_mfma_f32_16x16x32_bf16 v[44:47], v[154:157], v[190:193], v[44:47]
	v_mfma_f32_16x16x32_bf16 v[40:43], v[162:165], v[190:193], v[40:43]
	v_mfma_f32_16x16x32_bf16 v[28:31], v[154:157], v[202:205], v[28:31]
	v_mfma_f32_16x16x32_bf16 v[24:27], v[162:165], v[202:205], v[24:27]
	v_mfma_f32_16x16x32_bf16 v[12:15], v[154:157], v[210:213], v[12:15]
	v_mfma_f32_16x16x32_bf16 v[8:11], v[162:165], v[210:213], v[8:11]
	s_barrier
	s_add_u32 s56, s36, 0x160000
	s_addc_u32 s57, s37, 0
	s_add_i32 s58, s42, s22
	v_lshl_add_u64 v[140:141], s[56:57], 0, v[128:129]
	s_mov_b32 m0, s58
	s_nop 0
	global_load_lds_dwordx4 v[140:141], off
	v_lshl_add_u64 v[140:141], s[56:57], 0, v[130:131]
	s_add_i32 m0, s58, 0x2000
	s_nop 0
	global_load_lds_dwordx4 v[140:141], off
	s_waitcnt vmcnt(6)
	s_barrier
	v_mfma_f32_16x16x32_bf16 v[52:55], v[214:217], v[166:169], v[52:55]
	v_mfma_f32_16x16x32_bf16 v[48:51], v[222:225], v[166:169], v[48:51]
	v_mfma_f32_16x16x32_bf16 v[36:39], v[214:217], v[174:177], v[36:39]
	v_mfma_f32_16x16x32_bf16 v[32:35], v[222:225], v[174:177], v[32:35]
	v_mfma_f32_16x16x32_bf16 v[20:23], v[214:217], v[198:201], v[20:23]
	v_mfma_f32_16x16x32_bf16 v[16:19], v[222:225], v[198:201], v[16:19]
	v_mfma_f32_16x16x32_bf16 v[4:7], v[214:217], v[206:209], v[4:7]
	v_mfma_f32_16x16x32_bf16 v[0:3], v[222:225], v[206:209], v[0:3]
	v_mfma_f32_16x16x32_bf16 v[52:55], v[218:221], v[170:173], v[52:55]
	v_mfma_f32_16x16x32_bf16 v[48:51], v[226:229], v[170:173], v[48:51]
	v_mfma_f32_16x16x32_bf16 v[36:39], v[218:221], v[190:193], v[36:39]
	v_mfma_f32_16x16x32_bf16 v[32:35], v[226:229], v[190:193], v[32:35]
	v_mfma_f32_16x16x32_bf16 v[20:23], v[218:221], v[202:205], v[20:23]
	v_mfma_f32_16x16x32_bf16 v[16:19], v[226:229], v[202:205], v[16:19]
	v_mfma_f32_16x16x32_bf16 v[4:7], v[218:221], v[210:213], v[4:7]
	v_mfma_f32_16x16x32_bf16 v[0:3], v[226:229], v[210:213], v[0:3]
	s_add_i32 s56, 0, 0x18000
	v_add_u32_e32 v162, s56, v149
	s_barrier
	ds_read_b128 v[140:143], v162
	ds_read_b128 v[154:157], v162 offset:1024
	ds_read_b128 v[158:161], v162 offset:2048
	ds_read_b128 v[162:165], v162 offset:3072
	s_add_u32 s38, s38, 0x160000
	s_addc_u32 s39, s39, 0
	s_mov_b32 m0, s30
	v_lshl_add_u64 v[214:215], s[38:39], 0, v[128:129]
	ds_read_b128 v[166:169], v152 offset:32768
	ds_read_b128 v[170:173], v152 offset:33792
	ds_read_b128 v[174:177], v152 offset:34816
	ds_read_b128 v[190:193], v152 offset:35840
	ds_read_b128 v[198:201], v152 offset:36864
	ds_read_b128 v[202:205], v152 offset:37888
	ds_read_b128 v[206:209], v152 offset:38912
	ds_read_b128 v[210:213], v152 offset:39936
	global_load_lds_dwordx4 v[214:215], off
	v_lshl_add_u64 v[214:215], s[38:39], 0, v[130:131]
	s_mov_b32 m0, s31
	s_nop 0
	global_load_lds_dwordx4 v[214:215], off
	s_waitcnt lgkmcnt(8)
	s_barrier
; #define PG8_STAGE(bufoff, gbase, voff) do { _Pragma("unroll") for (int _i = 0; _i < 2; ++_i) \
;         __builtin_amdgcn_global_load_lds((const unsigned*)((const char*)(gbase) + (voff)[_i]), (LAS unsigned*)(lds + (bufoff) + ldsw + _i * 8192), 16, 0, 0); } while (0)
; #define PG8_LDA(dst, b, h) do { _Pragma("unroll") for (int m = 0; m < 4; ++m) _Pragma("unroll") for (int k = 0; k < 2; ++k) dst[m][k] = *(const LAS bf16x8*)(lds + PG8_SA(b, h) + aoff + m * 2048 + k * 1024); } while (0)
; #define PG8_LDB(dst, b, h) do { _Pragma("unroll") for (int n = 0; n < 2; ++n) _Pragma("unroll") for (int k = 0; k < 2; ++k) dst[n][k] = *(const LAS bf16x8*)(lds + PG8_SB(b, h) + boff + n * 2048 + k * 1024); } while (0)
; #define PG8_WAIT_V(n) asm volatile("s_waitcnt vmcnt(" #n ")" ::: "memory")
; #define PG8_WAIT_L(n) asm volatile("s_waitcnt lgkmcnt(" #n ")" ::: "memory")
; #define PG8_BAR __builtin_amdgcn_s_barrier()
; #define PG8_SCHED __builtin_amdgcn_sched_barrier(0)
; template <class Epi, class Sched>
; __device__ __forceinline__ void gemm_phase(LAS unsigned char* lds, const Gemm g, const Sched& S, const Epi& E) {
;     ...
;             PG8_LDB(B0, 0, 0); PG8_SCHED; PG8_LDA(At, 0, 0); PG8_STAGE(PG8_SA(1, 1), a1 + hstepA, voffA);
;             PG8_WAIT_L(8); PG8_BAR; PG8_WAIT_L(0); PG8_MMA(0, 0, At, B0); PG8_BAR; PG8_SCHED;
;             PG8_LDB(B1, 0, 1); PG8_STAGE(PG8_SB(0, 0), b2, voffB);
;             PG8_BAR; PG8_WAIT_L(0); PG8_MMA(0, 1, At, B1); PG8_BAR;
;             PG8_LDA(At, 0, 1); PG8_STAGE(PG8_SA(0, 0), a2, voffA);
;             PG8_BAR; PG8_WAIT_L(0); PG8_MMA(1, 0, At, B0); PG8_BAR; PG8_SCHED;
;             PG8_STAGE(PG8_SB(0, 1), b2 + hstepB, voffB);
;             PG8_WAIT_V(6); PG8_BAR; PG8_MMA(1, 1, At, B1); PG8_BAR;
;             PG8_LDB(B0, 1, 0); PG8_SCHED; PG8_LDA(At, 1, 0); PG8_STAGE(PG8_SA(0, 1), a2 + hstepA, voffA);
;             PG8_WAIT_L(8); PG8_BAR; PG8_WAIT_L(0); PG8_MMA(0, 0, At, B0); PG8_BAR; PG8_SCHED;
;             PG8_LDB(B1, 1, 1); PG8_STAGE(PG8_SB(1, 0), b3, voffB);
;             PG8_BAR; PG8_WAIT_L(0); PG8_MMA(0, 1, At, B1); PG8_BAR;
;             PG8_LDA(At, 1, 1); PG8_STAGE(PG8_SA(1, 0), a3, voffA);
;             PG8_BAR; PG8_WAIT_L(0); PG8_MMA(1, 0, At, B0); PG8_BAR; PG8_SCHED;
;             PG8_STAGE(PG8_SB(1, 1), b3 + hstepB, voffB);
;             PG8_WAIT_V(6); PG8_BAR; PG8_MMA(1, 1, At, B1); PG8_BAR;
	s_waitcnt lgkmcnt(0)
	s_waitcnt lgkmcnt(0)
	v_mfma_f32_16x16x32_bf16 v[124:127], v[140:143], v[166:169], v[124:127]
	v_mfma_f32_16x16x32_bf16 v[120:123], v[158:161], v[166:169], v[120:123]
	v_mfma_f32_16x16x32_bf16 v[108:111], v[140:143], v[174:177], v[108:111]
	v_mfma_f32_16x16x32_bf16 v[104:107], v[158:161], v[174:177], v[104:107]
	v_mfma_f32_16x16x32_bf16 v[92:95], v[140:143], v[198:201], v[92:95]
	v_mfma_f32_16x16x32_bf16 v[88:91], v[158:161], v[198:201], v[88:91]
	v_mfma_f32_16x16x32_bf16 v[76:79], v[140:143], v[206:209], v[76:79]
	v_mfma_f32_16x16x32_bf16 v[72:75], v[158:161], v[206:209], v[72:75]
	v_mfma_f32_16x16x32_bf16 v[124:127], v[154:157], v[170:173], v[124:127]
	v_mfma_f32_16x16x32_bf16 v[120:123], v[162:165], v[170:173], v[120:123]
	v_mfma_f32_16x16x32_bf16 v[108:111], v[154:157], v[190:193], v[108:111]
	v_mfma_f32_16x16x32_bf16 v[104:107], v[162:165], v[190:193], v[104:107]
	v_mfma_f32_16x16x32_bf16 v[92:95], v[154:157], v[202:205], v[92:95]
	v_mfma_f32_16x16x32_bf16 v[88:91], v[162:165], v[202:205], v[88:91]
	v_mfma_f32_16x16x32_bf16 v[76:79], v[154:157], v[210:213], v[76:79]
	v_mfma_f32_16x16x32_bf16 v[72:75], v[162:165], v[210:213], v[72:75]
	s_barrier
	s_add_i32 s38, 0, 0x1c000
	s_add_i32 s39, s56, s22
	v_add_u32_e32 v189, s38, v149
	v_lshl_add_u64 v[144:145], v[144:145], 0, s[16:17]
	s_mov_b32 m0, s39
	ds_read_b128 v[214:217], v189
	ds_read_b128 v[218:221], v189 offset:1024
	ds_read_b128 v[222:225], v189 offset:2048
	ds_read_b128 v[226:229], v189 offset:3072
	global_load_lds_dwordx4 v[144:145], off
	v_lshl_add_u64 v[144:145], v[178:179], 0, s[16:17]
	s_add_i32 m0, s39, 0x2000
	s_nop 0
	global_load_lds_dwordx4 v[144:145], off
	s_barrier
	s_waitcnt lgkmcnt(0)
	s_waitcnt lgkmcnt(0)
	v_mfma_f32_16x16x32_bf16 v[116:119], v[214:217], v[166:169], v[116:119]
	v_mfma_f32_16x16x32_bf16 v[112:115], v[222:225], v[166:169], v[112:115]
	v_mfma_f32_16x16x32_bf16 v[100:103], v[214:217], v[174:177], v[100:103]
	v_mfma_f32_16x16x32_bf16 v[96:99], v[222:225], v[174:177], v[96:99]
	v_mfma_f32_16x16x32_bf16 v[84:87], v[214:217], v[198:201], v[84:87]
	v_mfma_f32_16x16x32_bf16 v[80:83], v[222:225], v[198:201], v[80:83]
	v_mfma_f32_16x16x32_bf16 v[68:71], v[214:217], v[206:209], v[68:71]
	v_mfma_f32_16x16x32_bf16 v[64:67], v[222:225], v[206:209], v[64:67]
	v_mfma_f32_16x16x32_bf16 v[116:119], v[218:221], v[170:173], v[116:119]
	v_mfma_f32_16x16x32_bf16 v[112:115], v[226:229], v[170:173], v[112:115]
	v_mfma_f32_16x16x32_bf16 v[100:103], v[218:221], v[190:193], v[100:103]
	v_mfma_f32_16x16x32_bf16 v[96:99], v[226:229], v[190:193], v[96:99]
	v_mfma_f32_16x16x32_bf16 v[84:87], v[218:221], v[202:205], v[84:87]
	v_mfma_f32_16x16x32_bf16 v[80:83], v[226:229], v[202:205], v[80:83]
	v_mfma_f32_16x16x32_bf16 v[68:71], v[218:221], v[210:213], v[68:71]
	v_mfma_f32_16x16x32_bf16 v[64:67], v[226:229], v[210:213], v[64:67]
	s_mov_b32 m0, s34
	v_lshl_add_u64 v[144:145], v[194:195], 0, s[16:17]
	s_barrier
	ds_read_b128 v[166:169], v152 offset:49152
	ds_read_b128 v[170:173], v152 offset:50176
	ds_read_b128 v[174:177], v152 offset:51200
	ds_read_b128 v[190:193], v152 offset:52224
	ds_read_b128 v[198:201], v152 offset:53248
	ds_read_b128 v[202:205], v152 offset:54272
	ds_read_b128 v[206:209], v152 offset:55296
	ds_read_b128 v[210:213], v152 offset:56320
	global_load_lds_dwordx4 v[144:145], off
	v_lshl_add_u64 v[144:145], v[230:231], 0, s[16:17]
	s_mov_b32 m0, s35
	s_nop 0
	global_load_lds_dwordx4 v[144:145], off
	s_barrier
	s_waitcnt lgkmcnt(0)
	s_waitcnt lgkmcnt(0)
	v_mfma_f32_16x16x32_bf16 v[60:63], v[140:143], v[166:169], v[60:63]
	v_mfma_f32_16x16x32_bf16 v[56:59], v[158:161], v[166:169], v[56:59]
	v_mfma_f32_16x16x32_bf16 v[44:47], v[140:143], v[174:177], v[44:47]
	v_mfma_f32_16x16x32_bf16 v[40:43], v[158:161], v[174:177], v[40:43]
	v_mfma_f32_16x16x32_bf16 v[28:31], v[140:143], v[198:201], v[28:31]
	v_mfma_f32_16x16x32_bf16 v[24:27], v[158:161], v[198:201], v[24:27]
	v_mfma_f32_16x16x32_bf16 v[12:15], v[140:143], v[206:209], v[12:15]
	v_mfma_f32_16x16x32_bf16 v[8:11], v[158:161], v[206:209], v[8:11]
	v_mfma_f32_16x16x32_bf16 v[60:63], v[154:157], v[170:173], v[60:63]
	v_mfma_f32_16x16x32_bf16 v[56:59], v[162:165], v[170:173], v[56:59]
	v_mfma_f32_16x16x32_bf16 v[44:47], v[154:157], v[190:193], v[44:47]
	v_mfma_f32_16x16x32_bf16 v[40:43], v[162:165], v[190:193], v[40:43]
	v_mfma_f32_16x16x32_bf16 v[28:31], v[154:157], v[202:205], v[28:31]
	v_mfma_f32_16x16x32_bf16 v[24:27], v[162:165], v[202:205], v[24:27]
	v_mfma_f32_16x16x32_bf16 v[12:15], v[154:157], v[210:213], v[12:15]
	v_mfma_f32_16x16x32_bf16 v[8:11], v[162:165], v[210:213], v[8:11]
	s_barrier
	s_add_u32 s36, s36, 0x160080
	s_addc_u32 s37, s37, 0
	s_add_i32 s38, s38, s22
	v_lshl_add_u64 v[140:141], s[36:37], 0, v[128:129]
	s_mov_b32 m0, s38
	s_nop 0
	global_load_lds_dwordx4 v[140:141], off
	v_lshl_add_u64 v[140:141], s[36:37], 0, v[130:131]
	s_add_i32 m0, s38, 0x2000
	s_nop 0
	global_load_lds_dwordx4 v[140:141], off
	s_waitcnt vmcnt(6)
	s_barrier
	v_mfma_f32_16x16x32_bf16 v[52:55], v[214:217], v[166:169], v[52:55]
	v_mfma_f32_16x16x32_bf16 v[48:51], v[222:225], v[166:169], v[48:51]
	v_mfma_f32_16x16x32_bf16 v[36:39], v[214:217], v[174:177], v[36:39]
	v_mfma_f32_16x16x32_bf16 v[32:35], v[222:225], v[174:177], v[32:35]
	v_mfma_f32_16x16x32_bf16 v[20:23], v[214:217], v[198:201], v[20:23]
	v_mfma_f32_16x16x32_bf16 v[16:19], v[222:225], v[198:201], v[16:19]
	v_mfma_f32_16x16x32_bf16 v[4:7], v[214:217], v[206:209], v[4:7]
	v_mfma_f32_16x16x32_bf16 v[0:3], v[222:225], v[206:209], v[0:3]
	v_mfma_f32_16x16x32_bf16 v[52:55], v[218:221], v[170:173], v[52:55]
	v_mfma_f32_16x16x32_bf16 v[48:51], v[226:229], v[170:173], v[48:51]
	v_mfma_f32_16x16x32_bf16 v[36:39], v[218:221], v[190:193], v[36:39]
	v_mfma_f32_16x16x32_bf16 v[32:35], v[226:229], v[190:193], v[32:35]
	v_mfma_f32_16x16x32_bf16 v[20:23], v[218:221], v[202:205], v[20:23]
	v_mfma_f32_16x16x32_bf16 v[16:19], v[226:229], v[202:205], v[16:19]
	v_mfma_f32_16x16x32_bf16 v[4:7], v[218:221], v[210:213], v[4:7]
	v_mfma_f32_16x16x32_bf16 v[0:3], v[226:229], v[210:213], v[0:3]
	s_add_i32 s55, s55, 2
	s_add_u32 s26, s26, 0x100
	s_addc_u32 s27, s27, 0
	s_add_u32 s4, s4, 0x100
	s_addc_u32 s5, s5, 0
	s_cmpk_gt_u32 s55, 0x55
	s_barrier
;     __device__ __forceinline__ void operator()(const f32x4 (&acc)[2][2][4][2], const Unit& u, int wr, int wc, int fr, int fq) const {
;         const int row0 = u.pm * 256 + wr * 64 + fr, col0 = u.pn * 256 + wc * 32 + 4 * fq;
; #pragma unroll
;         for (int ai = 0; ai < 2; ++ai)
; #pragma unroll
;             for (int m = 0; m < 4; ++m) {
;                 const int row = row0 + ai * 128 + m * 16;
; #pragma unroll
;                 for (int bj = 0; bj < 2; ++bj)
; #pragma unroll
;                     for (int n = 0; n < 2; ++n) {
;                         const int c = col0 + bj * 128 + n * 16; float* p = out + (size_t)row * D + c;
;                         *(f32x4*)p = acc[ai][bj][m][n] + *(const f32x4*)p;
;                     }
;             }
;     }
	s_cbranch_scc0 .LBB0_1289
	s_setprio 0
	v_lshl_add_u32 v144, s53, 8, v148
	v_lshl_or_b32 v140, s54, 8, v150
	v_ashrrev_i32_e32 v145, 31, v144
	v_lshlrev_b64 v[142:143], 13, v[144:145]
	v_ashrrev_i32_e32 v141, 31, v140
	v_lshl_add_u64 v[154:155], s[88:89], 0, v[142:143]
	v_lshlrev_b64 v[142:143], 2, v[140:141]
	v_lshl_add_u64 v[140:141], v[154:155], 0, v[142:143]
	global_load_dwordx4 v[154:157], v[140:141], off
	s_mov_b32 s54, s51
	s_mov_b32 s53, s52
	s_mov_b64 s[36:37], s[10:11]
	s_mov_b64 s[26:27], s[8:9]
	s_waitcnt vmcnt(0)
	v_pk_add_f32 v[126:127], v[126:127], v[156:157]
	v_pk_add_f32 v[124:125], v[124:125], v[154:155]
	global_store_dwordx4 v[140:141], v[124:127], off
	global_load_dwordx4 v[124:127], v[140:141], off offset:64
	s_waitcnt vmcnt(0)
	v_pk_add_f32 v[122:123], v[122:123], v[126:127]
	v_pk_add_f32 v[120:121], v[120:121], v[124:125]
	global_store_dwordx4 v[140:141], v[120:123], off offset:64
	global_load_dwordx4 v[120:123], v[140:141], off offset:512
	s_waitcnt vmcnt(0)
	v_pk_add_f32 v[118:119], v[118:119], v[122:123]
	v_pk_add_f32 v[116:117], v[116:117], v[120:121]
	global_store_dwordx4 v[140:141], v[116:119], off offset:512
	global_load_dwordx4 v[116:119], v[140:141], off offset:576
	s_waitcnt vmcnt(0)
	v_pk_add_f32 v[114:115], v[114:115], v[118:119]
	v_pk_add_f32 v[112:113], v[112:113], v[116:117]
	global_store_dwordx4 v[140:141], v[112:115], off offset:576
	s_nop 1
	v_or_b32_e32 v112, 16, v144
	v_ashrrev_i32_e32 v113, 31, v112
	v_lshlrev_b64 v[112:113], 13, v[112:113]
	v_lshl_add_u64 v[112:113], s[88:89], 0, v[112:113]
	v_lshl_add_u64 v[116:117], v[112:113], 0, v[142:143]
	global_load_dwordx4 v[112:115], v[116:117], off
	s_waitcnt vmcnt(0)
	v_pk_add_f32 v[110:111], v[110:111], v[114:115]
	v_pk_add_f32 v[108:109], v[108:109], v[112:113]
	global_store_dwordx4 v[116:117], v[108:111], off
	global_load_dwordx4 v[108:111], v[116:117], off offset:64
	s_waitcnt vmcnt(0)
	v_pk_add_f32 v[106:107], v[106:107], v[110:111]
	v_pk_add_f32 v[104:105], v[104:105], v[108:109]
	global_store_dwordx4 v[116:117], v[104:107], off offset:64
	global_load_dwordx4 v[104:107], v[116:117], off offset:512
	s_waitcnt vmcnt(0)
	v_pk_add_f32 v[102:103], v[102:103], v[106:107]
	v_pk_add_f32 v[100:101], v[100:101], v[104:105]
	global_store_dwordx4 v[116:117], v[100:103], off offset:512
	global_load_dwordx4 v[100:103], v[116:117], off offset:576
	s_waitcnt vmcnt(0)
	v_pk_add_f32 v[98:99], v[98:99], v[102:103]
	v_pk_add_f32 v[96:97], v[96:97], v[100:101]
	global_store_dwordx4 v[116:117], v[96:99], off offset:576
	s_nop 1
	v_or_b32_e32 v96, 32, v144
	v_ashrrev_i32_e32 v97, 31, v96
	v_lshlrev_b64 v[96:97], 13, v[96:97]
	v_lshl_add_u64 v[96:97], s[88:89], 0, v[96:97]
	v_lshl_add_u64 v[100:101], v[96:97], 0, v[142:143]
	global_load_dwordx4 v[96:99], v[100:101], off
	s_waitcnt vmcnt(0)
	v_pk_add_f32 v[94:95], v[94:95], v[98:99]
	v_pk_add_f32 v[92:93], v[92:93], v[96:97]
	global_store_dwordx4 v[100:101], v[92:95], off
	global_load_dwordx4 v[92:95], v[100:101], off offset:64
	s_waitcnt vmcnt(0)
	v_pk_add_f32 v[90:91], v[90:91], v[94:95]
	v_pk_add_f32 v[88:89], v[88:89], v[92:93]
	global_store_dwordx4 v[100:101], v[88:91], off offset:64
	global_load_dwordx4 v[88:91], v[100:101], off offset:512
	s_waitcnt vmcnt(0)
	v_pk_add_f32 v[86:87], v[86:87], v[90:91]
	v_pk_add_f32 v[84:85], v[84:85], v[88:89]
	global_store_dwordx4 v[100:101], v[84:87], off offset:512
	global_load_dwordx4 v[84:87], v[100:101], off offset:576
	s_waitcnt vmcnt(0)
	v_pk_add_f32 v[82:83], v[82:83], v[86:87]
	v_pk_add_f32 v[80:81], v[80:81], v[84:85]
	global_store_dwordx4 v[100:101], v[80:83], off offset:576
	s_nop 1
	v_or_b32_e32 v80, 48, v144
	v_ashrrev_i32_e32 v81, 31, v80
	v_lshlrev_b64 v[80:81], 13, v[80:81]
	v_lshl_add_u64 v[80:81], s[88:89], 0, v[80:81]
	v_lshl_add_u64 v[84:85], v[80:81], 0, v[142:143]
	global_load_dwordx4 v[80:83], v[84:85], off
	s_waitcnt vmcnt(0)
	v_pk_add_f32 v[78:79], v[78:79], v[82:83]
	v_pk_add_f32 v[76:77], v[76:77], v[80:81]
	global_store_dwordx4 v[84:85], v[76:79], off
	global_load_dwordx4 v[76:79], v[84:85], off offset:64
	s_waitcnt vmcnt(0)
	v_pk_add_f32 v[74:75], v[74:75], v[78:79]
	v_pk_add_f32 v[72:73], v[72:73], v[76:77]
	global_store_dwordx4 v[84:85], v[72:75], off offset:64
	global_load_dwordx4 v[72:75], v[84:85], off offset:512
	s_waitcnt vmcnt(0)
;     __device__ __forceinline__ void operator()(const f32x4 (&acc)[2][2][4][2], const Unit& u, int wr, int wc, int fr, int fq) const {
;         const int row0 = u.pm * 256 + wr * 64 + fr, col0 = u.pn * 256 + wc * 32 + 4 * fq;
; #pragma unroll
;         for (int ai = 0; ai < 2; ++ai)
; #pragma unroll
;             for (int m = 0; m < 4; ++m) {
;                 const int row = row0 + ai * 128 + m * 16;
; #pragma unroll
;                 for (int bj = 0; bj < 2; ++bj)
; #pragma unroll
;                     for (int n = 0; n < 2; ++n) {
;                         const int c = col0 + bj * 128 + n * 16; float* p = out + (size_t)row * D + c;
;                         *(f32x4*)p = acc[ai][bj][m][n] + *(const f32x4*)p;
;                     }
;             }
;     }
	v_pk_add_f32 v[70:71], v[70:71], v[74:75]
	v_pk_add_f32 v[68:69], v[68:69], v[72:73]
	global_store_dwordx4 v[84:85], v[68:71], off offset:512
	global_load_dwordx4 v[68:71], v[84:85], off offset:576
	s_waitcnt vmcnt(0)
	v_pk_add_f32 v[66:67], v[66:67], v[70:71]
	v_add_co_u32_e32 v70, vcc, s43, v140
	v_pk_add_f32 v[64:65], v[64:65], v[68:69]
	s_nop 0
	v_addc_co_u32_e32 v71, vcc, 0, v141, vcc
	global_store_dwordx4 v[84:85], v[64:67], off offset:576
	global_load_dwordx4 v[64:67], v[70:71], off
	v_lshl_add_u64 v[68:69], v[140:141], 0, s[18:19]
	s_waitcnt vmcnt(0)
	v_pk_add_f32 v[62:63], v[62:63], v[66:67]
	v_pk_add_f32 v[60:61], v[60:61], v[64:65]
	global_store_dwordx4 v[70:71], v[60:63], off
	global_load_dwordx4 v[60:63], v[68:69], off offset:64
	s_waitcnt vmcnt(0)
	v_pk_add_f32 v[58:59], v[58:59], v[62:63]
	v_pk_add_f32 v[56:57], v[56:57], v[60:61]
	global_store_dwordx4 v[68:69], v[56:59], off offset:64
	global_load_dwordx4 v[56:59], v[68:69], off offset:512
	s_waitcnt vmcnt(0)
	v_pk_add_f32 v[54:55], v[54:55], v[58:59]
	v_pk_add_f32 v[52:53], v[52:53], v[56:57]
	global_store_dwordx4 v[68:69], v[52:55], off offset:512
	global_load_dwordx4 v[52:55], v[68:69], off offset:576
	s_waitcnt vmcnt(0)
	v_pk_add_f32 v[50:51], v[50:51], v[54:55]
	v_add_co_u32_e32 v54, vcc, s44, v140
	v_pk_add_f32 v[48:49], v[48:49], v[52:53]
	s_nop 0
	v_addc_co_u32_e32 v55, vcc, 0, v141, vcc
	global_store_dwordx4 v[68:69], v[48:51], off offset:576
	global_load_dwordx4 v[48:51], v[54:55], off
	v_lshl_add_u64 v[52:53], v[140:141], 0, s[20:21]
	s_waitcnt vmcnt(0)
	v_pk_add_f32 v[46:47], v[46:47], v[50:51]
	v_pk_add_f32 v[44:45], v[44:45], v[48:49]
	global_store_dwordx4 v[54:55], v[44:47], off
	global_load_dwordx4 v[44:47], v[52:53], off offset:64
	s_waitcnt vmcnt(0)
	v_pk_add_f32 v[42:43], v[42:43], v[46:47]
	v_pk_add_f32 v[40:41], v[40:41], v[44:45]
	global_store_dwordx4 v[52:53], v[40:43], off offset:64
	global_load_dwordx4 v[40:43], v[52:53], off offset:512
	s_waitcnt vmcnt(0)
	v_pk_add_f32 v[38:39], v[38:39], v[42:43]
	v_pk_add_f32 v[36:37], v[36:37], v[40:41]
	global_store_dwordx4 v[52:53], v[36:39], off offset:512
	global_load_dwordx4 v[36:39], v[52:53], off offset:576
	s_waitcnt vmcnt(0)
	v_pk_add_f32 v[34:35], v[34:35], v[38:39]
	v_add_co_u32_e32 v38, vcc, s45, v140
	v_pk_add_f32 v[32:33], v[32:33], v[36:37]
	s_nop 0
	v_addc_co_u32_e32 v39, vcc, 0, v141, vcc
	global_store_dwordx4 v[52:53], v[32:35], off offset:576
	global_load_dwordx4 v[32:35], v[38:39], off
	v_lshl_add_u64 v[36:37], v[140:141], 0, s[24:25]
	s_waitcnt vmcnt(0)
	v_pk_add_f32 v[30:31], v[30:31], v[34:35]
	v_pk_add_f32 v[28:29], v[28:29], v[32:33]
	global_store_dwordx4 v[38:39], v[28:31], off
	global_load_dwordx4 v[28:31], v[36:37], off offset:64
	s_waitcnt vmcnt(0)
	v_pk_add_f32 v[26:27], v[26:27], v[30:31]
	v_pk_add_f32 v[24:25], v[24:25], v[28:29]
	global_store_dwordx4 v[36:37], v[24:27], off offset:64
	global_load_dwordx4 v[24:27], v[36:37], off offset:512
	s_waitcnt vmcnt(0)
	v_pk_add_f32 v[22:23], v[22:23], v[26:27]
	v_pk_add_f32 v[20:21], v[20:21], v[24:25]
	global_store_dwordx4 v[36:37], v[20:23], off offset:512
	global_load_dwordx4 v[20:23], v[36:37], off offset:576
	s_waitcnt vmcnt(0)
	v_pk_add_f32 v[18:19], v[18:19], v[22:23]
	v_add_co_u32_e32 v22, vcc, s50, v140
	v_pk_add_f32 v[16:17], v[16:17], v[20:21]
	s_nop 0
	v_addc_co_u32_e32 v23, vcc, 0, v141, vcc
	global_store_dwordx4 v[36:37], v[16:19], off offset:576
	global_load_dwordx4 v[18:21], v[22:23], off
	s_and_b64 vcc, exec, s[6:7]
	v_lshl_add_u64 v[16:17], v[140:141], 0, s[12:13]
	s_waitcnt vmcnt(0)
	v_pk_add_f32 v[14:15], v[14:15], v[20:21]
	v_pk_add_f32 v[12:13], v[12:13], v[18:19]
	global_store_dwordx4 v[22:23], v[12:15], off
	global_load_dwordx4 v[12:15], v[16:17], off offset:64
	s_waitcnt vmcnt(0)
	v_pk_add_f32 v[10:11], v[10:11], v[14:15]
	v_pk_add_f32 v[8:9], v[8:9], v[12:13]
	global_store_dwordx4 v[16:17], v[8:11], off offset:64
	global_load_dwordx4 v[8:11], v[16:17], off offset:512
	s_waitcnt vmcnt(0)
	v_pk_add_f32 v[6:7], v[6:7], v[10:11]
	v_pk_add_f32 v[4:5], v[4:5], v[8:9]
	global_store_dwordx4 v[16:17], v[4:7], off offset:512
	global_load_dwordx4 v[4:7], v[16:17], off offset:576
	s_waitcnt vmcnt(0)
	v_pk_add_f32 v[2:3], v[2:3], v[6:7]
	v_pk_add_f32 v[0:1], v[0:1], v[4:5]
	global_store_dwordx4 v[16:17], v[0:3], off offset:576
	s_cbranch_vccz .LBB0_1278
	s_waitcnt vmcnt(0)
	s_cmpk_gt_u32 s14, 0xff
	s_cbranch_scc1 .LBB0_1293
	s_barrier
